# v5 + attention PV reordered key-step-major with four V-fragment buffers (LDS transpose reads run three MFMA pairs ahead); per-accumulator order unchanged
# speedup vs baseline: 1.0173x; 1.0052x over previous
; __device__ __forceinline__ void partialSM(f32x16& p0, f32x16& p1, float& m_reg, float& mn, float& alpha) {
;     ...
;   float mnC = -mn * C;
; #pragma unroll
;   for (int r = 0; r < 16; ++r) p0[r] = fmaf(p0[r], C, mnC);
; #pragma unroll
;   for (int r = 0; r < 16; ++r) p1[r] = fmaf(p1[r], C, mnC);
; #pragma unroll
;   for (int r = 0; r < 16; ++r) p0[r] = __builtin_amdgcn_exp2f(p0[r]);
; }
; __device__ __forceinline__ void finishSM(f32x16& p0, f32x16& p1, float alpha, float& l_reg, bf16x8& pa0, bf16x8& pa1, bf16x8& pa2, bf16x8& pa3) {
; #pragma unroll
;   for (int r = 0; r < 16; ++r) p1[r] = __builtin_amdgcn_exp2f(p1[r]);
;   float ps = 0;
; #pragma unroll
;   for (int r = 0; r < 16; ++r) ps += p0[r];
; #pragma unroll
;   for (int r = 0; r < 16; ++r) ps += p1[r];
;   { auto rr = __builtin_amdgcn_permlane32_swap(__float_as_uint(ps), __float_as_uint(ps), false, false);
;     ps = __uint_as_float(rr[0]) + __uint_as_float(rr[1]); }
;   l_reg = l_reg * alpha + ps;
;     ...
;   PK4(p0, 0, pa0); PK4(p0, 8, pa1); PK4(p1, 0, pa2); PK4(p1, 8, pa3);
.LBB0_624:
	v_cndmask_b32_e64 v243, v245, v243, s[8:9]
	v_mul_f32_e32 v194, 0xbe0293ee, v243
	v_fmamk_f32 v146, v146, 0x3e0293ee, v194
	v_fmamk_f32 v147, v147, 0x3e0293ee, v194
	v_fmamk_f32 v148, v148, 0x3e0293ee, v194
	v_fmamk_f32 v149, v149, 0x3e0293ee, v194
	v_fmamk_f32 v150, v150, 0x3e0293ee, v194
	v_fmamk_f32 v151, v151, 0x3e0293ee, v194
	v_fmamk_f32 v152, v152, 0x3e0293ee, v194
	v_fmamk_f32 v153, v153, 0x3e0293ee, v194
	v_fmamk_f32 v154, v154, 0x3e0293ee, v194
	v_fmamk_f32 v155, v155, 0x3e0293ee, v194
	v_fmamk_f32 v156, v156, 0x3e0293ee, v194
	v_fmamk_f32 v157, v157, 0x3e0293ee, v194
	v_fmamk_f32 v158, v158, 0x3e0293ee, v194
	v_fmamk_f32 v159, v159, 0x3e0293ee, v194
	v_fmamk_f32 v160, v160, 0x3e0293ee, v194
	v_fmamk_f32 v161, v161, 0x3e0293ee, v194
	v_fmamk_f32 v130, v130, 0x3e0293ee, v194
	v_fmamk_f32 v131, v131, 0x3e0293ee, v194
	v_fmamk_f32 v132, v132, 0x3e0293ee, v194
	v_fmamk_f32 v133, v133, 0x3e0293ee, v194
	v_fmamk_f32 v134, v134, 0x3e0293ee, v194
	v_fmamk_f32 v135, v135, 0x3e0293ee, v194
	v_fmamk_f32 v136, v136, 0x3e0293ee, v194
	v_fmamk_f32 v137, v137, 0x3e0293ee, v194
	v_fmamk_f32 v138, v138, 0x3e0293ee, v194
	v_fmamk_f32 v139, v139, 0x3e0293ee, v194
	v_fmamk_f32 v140, v140, 0x3e0293ee, v194
	v_fmamk_f32 v141, v141, 0x3e0293ee, v194
	v_fmamk_f32 v142, v142, 0x3e0293ee, v194
	v_fmamk_f32 v143, v143, 0x3e0293ee, v194
	v_fmamk_f32 v144, v144, 0x3e0293ee, v194
	v_fmac_f32_e32 v194, 0x3e0293ee, v145
	v_exp_f32_e32 v145, v146
	v_exp_f32_e32 v147, v147
	v_exp_f32_e32 v148, v148
	v_exp_f32_e32 v149, v149
	v_exp_f32_e32 v150, v150
	v_exp_f32_e32 v195, v130
	v_add_f32_e32 v130, 0, v145
	v_exp_f32_e32 v151, v151
	v_add_f32_e32 v130, v147, v130
	v_exp_f32_e32 v152, v152
	v_add_f32_e32 v130, v148, v130
	v_exp_f32_e32 v153, v153
	v_add_f32_e32 v130, v149, v130
	v_exp_f32_e32 v154, v154
	v_add_f32_e32 v130, v150, v130
	v_exp_f32_e32 v155, v155
	v_add_f32_e32 v130, v151, v130
	v_exp_f32_e32 v156, v156
	v_add_f32_e32 v130, v152, v130
	v_exp_f32_e32 v157, v157
	v_add_f32_e32 v130, v153, v130
	v_exp_f32_e32 v158, v158
	v_add_f32_e32 v130, v154, v130
	v_exp_f32_e32 v159, v159
	v_add_f32_e32 v130, v155, v130
	v_exp_f32_e32 v160, v160
	v_add_f32_e32 v130, v156, v130
	v_exp_f32_e32 v161, v161
	v_add_f32_e32 v130, v157, v130
	v_add_f32_e32 v130, v158, v130
	v_exp_f32_e32 v196, v131
	v_add_f32_e32 v130, v159, v130
	v_exp_f32_e32 v197, v132
	v_add_f32_e32 v130, v160, v130
	v_exp_f32_e32 v198, v133
	v_add_f32_e32 v130, v161, v130
	v_exp_f32_e32 v199, v134
	v_add_f32_e32 v130, v195, v130
	v_exp_f32_e32 v200, v135
	v_add_f32_e32 v130, v196, v130
	v_exp_f32_e32 v201, v136
	v_add_f32_e32 v130, v197, v130
	v_exp_f32_e32 v202, v137
	v_add_f32_e32 v130, v198, v130
	v_exp_f32_e32 v203, v138
	v_add_f32_e32 v130, v199, v130
	v_exp_f32_e32 v204, v139
	v_add_f32_e32 v130, v200, v130
	v_exp_f32_e32 v205, v140
	v_add_f32_e32 v130, v201, v130
	v_exp_f32_e32 v206, v141
	v_add_f32_e32 v130, v202, v130
	v_exp_f32_e32 v207, v142
	v_add_f32_e32 v130, v203, v130
	v_exp_f32_e32 v208, v143
	v_add_f32_e32 v130, v204, v130
	v_exp_f32_e32 v209, v144
	v_add_f32_e32 v130, v205, v130
	v_exp_f32_e32 v194, v194
	v_add_f32_e32 v130, v206, v130
	v_add_f32_e32 v130, v207, v130
	v_add_f32_e32 v130, v208, v130
	v_add_f32_e32 v130, v209, v130
	v_add_f32_e32 v130, v194, v130
	v_mov_b32_e32 v131, v130
	s_nop 1
	v_permlane32_swap_b32_e32 v130, v131
	v_add_f32_e32 v146, v130, v131
	v_fmac_f32_e32 v146, v244, v1
	v_cvt_pk_bf16_f32 v130, v145, v147
	v_cvt_pk_bf16_f32 v131, v148, v149
	v_cvt_pk_bf16_f32 v132, v150, v151
	v_cvt_pk_bf16_f32 v133, v152, v153
	v_cvt_pk_bf16_f32 v134, v154, v155
	v_cvt_pk_bf16_f32 v135, v156, v157
	v_cvt_pk_bf16_f32 v136, v158, v159
	v_cvt_pk_bf16_f32 v137, v160, v161
	v_cvt_pk_bf16_f32 v138, v195, v196
	v_cvt_pk_bf16_f32 v139, v197, v198
	v_cvt_pk_bf16_f32 v140, v199, v200
	v_cvt_pk_bf16_f32 v141, v201, v202
	v_cvt_pk_bf16_f32 v142, v203, v204
	v_cvt_pk_bf16_f32 v143, v205, v206
	v_cvt_pk_bf16_f32 v144, v207, v208
	v_cvt_pk_bf16_f32 v145, v209, v194
	s_nop 0
	v_permlane32_swap_b32_e32 v130, v132
	v_permlane32_swap_b32_e32 v131, v133
	v_permlane32_swap_b32_e32 v134, v136
	v_permlane32_swap_b32_e32 v135, v137
	v_permlane32_swap_b32_e32 v138, v140
	v_permlane32_swap_b32_e32 v139, v141
	v_permlane32_swap_b32_e32 v142, v144
	v_permlane32_swap_b32_e32 v143, v145
	v_lshl_add_u32 v1, s34, 15, v242
	ds_read_b64_tr_b16 v[148:149], v1 offset:0
	ds_read_b64_tr_b16 v[150:151], v1 offset:4096
	ds_read_b64_tr_b16 v[152:153], v1 offset:8192
	ds_read_b64_tr_b16 v[154:155], v1 offset:12288
	ds_read_b64_tr_b16 v[156:157], v1 offset:512
	ds_read_b64_tr_b16 v[158:159], v1 offset:4608
	ds_read_b64_tr_b16 v[194:195], v1 offset:8704
	ds_read_b64_tr_b16 v[196:197], v1 offset:12800
	ds_read_b64_tr_b16 v[198:199], v1 offset:1024
	ds_read_b64_tr_b16 v[200:201], v1 offset:5120
	ds_read_b64_tr_b16 v[202:203], v1 offset:9216
	ds_read_b64_tr_b16 v[204:205], v1 offset:13312
	s_waitcnt lgkmcnt(8)
; #define SBAR() __builtin_amdgcn_sched_barrier(0)
; #define STEP(D, CUR, NXT) v_load<D + 1>(NXT, vb); asm volatile("s_waitcnt lgkmcnt(8)" ::: "memory"); SBAR(); pv_mma(o[D], CUR, pa0, pa1, pa2, pa3); SBAR();
; __device__ __forceinline__ void pv_mma(f32x16& od, const VFrag& f, bf16x8 pa0, bf16x8 pa1, bf16x8 pa2, bf16x8 pa3) {
;     ...
;   od = __builtin_amdgcn_mfma_f32_32x32x16_bf16(pa0, PK(f.l0, f.h0), od, 0, 0, 0);
;   od = __builtin_amdgcn_mfma_f32_32x32x16_bf16(pa1, PK(f.l1, f.h1), od, 0, 0, 0);
;   od = __builtin_amdgcn_mfma_f32_32x32x16_bf16(pa2, PK(f.l2, f.h2), od, 0, 0, 0);
;   od = __builtin_amdgcn_mfma_f32_32x32x16_bf16(pa3, PK(f.l3, f.h3), od, 0, 0, 0);
;     ...
; }
; __device__ __forceinline__ void pv_all(f32x16* o, int vb, bf16x8 pa0, bf16x8 pa1, bf16x8 pa2, bf16x8 pa3) {
;   VFrag fa, fb;
;   v_load<0>(fa, vb);
;     ...
;   STEP(0, fa, fb) STEP(1, fb, fa) STEP(2, fa, fb) STEP(3, fb, fa) STEP(4, fa, fb) STEP(5, fb, fa) STEP(6, fa, fb)
;     ...
;   asm volatile("s_waitcnt lgkmcnt(0)" ::: "memory"); SBAR(); pv_mma(o[7], fb, pa0, pa1, pa2, pa3);
; }
	v_mfma_f32_32x32x16_bf16 v[114:129], v[130:133], v[148:151], v[114:129]
	ds_read_b64_tr_b16 v[206:207], v1 offset:1536
	ds_read_b64_tr_b16 v[208:209], v1 offset:5632
	ds_read_b64_tr_b16 v[244:245], v1 offset:9728
	ds_read_b64_tr_b16 v[246:247], v1 offset:13824
	v_mfma_f32_32x32x16_bf16 v[114:129], v[134:137], v[152:155], v[114:129]
	s_waitcnt lgkmcnt(8)
	v_mfma_f32_32x32x16_bf16 v[98:113], v[130:133], v[156:159], v[98:113]
	ds_read_b64_tr_b16 v[148:149], v1 offset:2048
	ds_read_b64_tr_b16 v[150:151], v1 offset:6144
	ds_read_b64_tr_b16 v[152:153], v1 offset:10240
	ds_read_b64_tr_b16 v[154:155], v1 offset:14336
	v_mfma_f32_32x32x16_bf16 v[98:113], v[134:137], v[194:197], v[98:113]
	s_waitcnt lgkmcnt(8)
	v_mfma_f32_32x32x16_bf16 v[82:97], v[130:133], v[198:201], v[82:97]
	ds_read_b64_tr_b16 v[156:157], v1 offset:2560
	ds_read_b64_tr_b16 v[158:159], v1 offset:6656
	ds_read_b64_tr_b16 v[194:195], v1 offset:10752
	ds_read_b64_tr_b16 v[196:197], v1 offset:14848
	v_mfma_f32_32x32x16_bf16 v[82:97], v[134:137], v[202:205], v[82:97]
	s_waitcnt lgkmcnt(8)
	v_mfma_f32_32x32x16_bf16 v[66:81], v[130:133], v[206:209], v[66:81]
	ds_read_b64_tr_b16 v[198:199], v1 offset:3072
	ds_read_b64_tr_b16 v[200:201], v1 offset:7168
	ds_read_b64_tr_b16 v[202:203], v1 offset:11264
	ds_read_b64_tr_b16 v[204:205], v1 offset:15360
	v_mfma_f32_32x32x16_bf16 v[66:81], v[134:137], v[244:247], v[66:81]
	s_waitcnt lgkmcnt(8)
	v_mfma_f32_32x32x16_bf16 v[50:65], v[130:133], v[148:151], v[50:65]
	ds_read_b64_tr_b16 v[206:207], v1 offset:3584
	ds_read_b64_tr_b16 v[208:209], v1 offset:7680
	ds_read_b64_tr_b16 v[244:245], v1 offset:11776
	ds_read_b64_tr_b16 v[246:247], v1 offset:15872
	v_mfma_f32_32x32x16_bf16 v[50:65], v[134:137], v[152:155], v[50:65]
	s_waitcnt lgkmcnt(8)
	v_mfma_f32_32x32x16_bf16 v[34:49], v[130:133], v[156:159], v[34:49]
	ds_read_b64_tr_b16 v[148:149], v1 offset:16384
	ds_read_b64_tr_b16 v[150:151], v1 offset:20480
	ds_read_b64_tr_b16 v[152:153], v1 offset:24576
	ds_read_b64_tr_b16 v[154:155], v1 offset:28672
	v_mfma_f32_32x32x16_bf16 v[34:49], v[134:137], v[194:197], v[34:49]
	s_waitcnt lgkmcnt(8)
	v_mfma_f32_32x32x16_bf16 v[18:33], v[130:133], v[198:201], v[18:33]
	ds_read_b64_tr_b16 v[156:157], v1 offset:16896
	ds_read_b64_tr_b16 v[158:159], v1 offset:20992
	ds_read_b64_tr_b16 v[194:195], v1 offset:25088
	ds_read_b64_tr_b16 v[196:197], v1 offset:29184
	v_mfma_f32_32x32x16_bf16 v[18:33], v[134:137], v[202:205], v[18:33]
	s_waitcnt lgkmcnt(8)
	v_mfma_f32_32x32x16_bf16 v[2:17], v[130:133], v[206:209], v[2:17]
	ds_read_b64_tr_b16 v[198:199], v1 offset:17408
	ds_read_b64_tr_b16 v[200:201], v1 offset:21504
	ds_read_b64_tr_b16 v[202:203], v1 offset:25600
	ds_read_b64_tr_b16 v[204:205], v1 offset:29696
	v_mfma_f32_32x32x16_bf16 v[2:17], v[134:137], v[244:247], v[2:17]
	s_waitcnt lgkmcnt(8)
	v_mfma_f32_32x32x16_bf16 v[114:129], v[138:141], v[148:151], v[114:129]
	ds_read_b64_tr_b16 v[206:207], v1 offset:17920
	ds_read_b64_tr_b16 v[208:209], v1 offset:22016
	ds_read_b64_tr_b16 v[244:245], v1 offset:26112
	ds_read_b64_tr_b16 v[246:247], v1 offset:30208
	v_mfma_f32_32x32x16_bf16 v[114:129], v[142:145], v[152:155], v[114:129]
	s_waitcnt lgkmcnt(8)
	v_mfma_f32_32x32x16_bf16 v[98:113], v[138:141], v[156:159], v[98:113]
	ds_read_b64_tr_b16 v[148:149], v1 offset:18432
	ds_read_b64_tr_b16 v[150:151], v1 offset:22528
	ds_read_b64_tr_b16 v[152:153], v1 offset:26624
	ds_read_b64_tr_b16 v[154:155], v1 offset:30720
	v_mfma_f32_32x32x16_bf16 v[98:113], v[142:145], v[194:197], v[98:113]
	s_waitcnt lgkmcnt(8)
	v_mfma_f32_32x32x16_bf16 v[82:97], v[138:141], v[198:201], v[82:97]
	ds_read_b64_tr_b16 v[156:157], v1 offset:18944
	ds_read_b64_tr_b16 v[158:159], v1 offset:23040
	ds_read_b64_tr_b16 v[194:195], v1 offset:27136
	ds_read_b64_tr_b16 v[196:197], v1 offset:31232
	v_mfma_f32_32x32x16_bf16 v[82:97], v[142:145], v[202:205], v[82:97]
	s_waitcnt lgkmcnt(8)
	v_mfma_f32_32x32x16_bf16 v[66:81], v[138:141], v[206:209], v[66:81]
	ds_read_b64_tr_b16 v[198:199], v1 offset:19456
	ds_read_b64_tr_b16 v[200:201], v1 offset:23552
	ds_read_b64_tr_b16 v[202:203], v1 offset:27648
	ds_read_b64_tr_b16 v[204:205], v1 offset:31744
	v_mfma_f32_32x32x16_bf16 v[66:81], v[142:145], v[244:247], v[66:81]
	s_waitcnt lgkmcnt(8)
	v_mfma_f32_32x32x16_bf16 v[50:65], v[138:141], v[148:151], v[50:65]
	ds_read_b64_tr_b16 v[206:207], v1 offset:19968
	ds_read_b64_tr_b16 v[208:209], v1 offset:24064
	ds_read_b64_tr_b16 v[244:245], v1 offset:28160
	ds_read_b64_tr_b16 v[246:247], v1 offset:32256
	v_mfma_f32_32x32x16_bf16 v[50:65], v[142:145], v[152:155], v[50:65]
	s_waitcnt lgkmcnt(8)
	v_mfma_f32_32x32x16_bf16 v[34:49], v[138:141], v[156:159], v[34:49]
	v_mfma_f32_32x32x16_bf16 v[34:49], v[142:145], v[194:197], v[34:49]
	s_waitcnt lgkmcnt(4)
	v_mfma_f32_32x32x16_bf16 v[18:33], v[138:141], v[198:201], v[18:33]
	v_mfma_f32_32x32x16_bf16 v[18:33], v[142:145], v[202:205], v[18:33]
	s_waitcnt vmcnt(0) lgkmcnt(0)
	s_barrier
	s_addk_i32 s33, 0x4000
	s_cmp_eq_u32 s24, s29
	v_mfma_f32_32x32x16_bf16 v[2:17], v[138:141], v[206:209], v[2:17]
	v_mfma_f32_32x32x16_bf16 v[2:17], v[142:145], v[244:247], v[2:17]
	s_cbranch_scc1 .LBB0_626
	v_mov_b32_e32 v244, v146
	s_branch .LBB0_616
